# P6: per-row q and c of the SwiGLU epilogue computed once per tile inside the K loop (load-phase slack) instead of in the epilogue
# speedup vs baseline: 1.0062x; 1.0027x over previous
.LBB0_686:
	s_cmp_lg_u32 s59, 4
	s_cbranch_scc1 .Lp6_pre_skip
	v_fmamk_f32 v166, v166, 0x3a800000, v151
	v_rsq_f32_e32 v244, v166
	v_fmamk_f32 v165, v165, 0x3a800000, v151
	v_rsq_f32_e32 v245, v165
	v_fmamk_f32 v164, v164, 0x3a800000, v151
	v_rsq_f32_e32 v246, v164
	v_fmamk_f32 v163, v163, 0x3a800000, v151
	v_rsq_f32_e32 v247, v163
	v_fmamk_f32 v162, v162, 0x3a800000, v151
	v_rsq_f32_e32 v248, v162
	v_fmamk_f32 v161, v161, 0x3a800000, v151
	v_rsq_f32_e32 v249, v161
	v_fmamk_f32 v152, v152, 0x3a800000, v151
	v_rsq_f32_e32 v250, v152
	v_fmamk_f32 v149, v149, 0x3a800000, v151
	v_rsq_f32_e32 v251, v149
	s_nop 0
	v_mul_f32_e32 v244, 0xbfb8aa3b, v244
	v_mul_f32_e32 v245, 0xbfb8aa3b, v245
	v_mul_f32_e32 v246, 0xbfb8aa3b, v246
	v_mul_f32_e32 v247, 0xbfb8aa3b, v247
	v_mul_f32_e32 v248, 0xbfb8aa3b, v248
	v_mul_f32_e32 v249, 0xbfb8aa3b, v249
	v_mul_f32_e32 v250, 0xbfb8aa3b, v250
	v_mul_f32_e32 v251, 0xbfb8aa3b, v251

.LBB0_690:
	v_pk_mul_f32 v[120:121], v[124:125], v[120:121]
	v_pk_mul_f32 v[122:123], v[126:127], v[122:123]
	v_pk_mul_f32 v[112:113], v[116:117], v[112:113]
	v_pk_mul_f32 v[168:169], v[244:245], v[124:125] op_sel_hi:[0,1]
	v_exp_f32_e32 v168, v168
	v_exp_f32_e32 v169, v169
	v_pk_mul_f32 v[124:125], v[244:245], v[126:127] op_sel_hi:[0,1]
	v_exp_f32_e32 v124, v124
	v_exp_f32_e32 v125, v125
	v_pk_fma_f32 v[168:169], v[168:169], v[166:167], v[166:167] op_sel_hi:[1,0,0]
	v_rcp_f32_e32 v168, v168
	v_rcp_f32_e32 v169, v169
	v_pk_fma_f32 v[124:125], v[124:125], v[166:167], v[166:167] op_sel_hi:[1,0,0]
	v_pk_mul_f32 v[114:115], v[118:119], v[114:115]
	v_rcp_f32_e32 v124, v124
	v_rcp_f32_e32 v125, v125
	v_pk_mul_f32 v[120:121], v[168:169], v[120:121]
	v_pk_mul_f32 v[126:127], v[244:245], v[116:117] op_sel_hi:[0,1]
	v_exp_f32_e32 v126, v126
	v_exp_f32_e32 v127, v127
	v_pk_mul_f32 v[122:123], v[124:125], v[122:123]
	v_pk_mul_f32 v[124:125], v[244:245], v[118:119] op_sel_hi:[0,1]
	v_exp_f32_e32 v124, v124
	v_exp_f32_e32 v125, v125
	v_cvt_pk_bf16_f32 v120, v120, v121
	v_cvt_pk_bf16_f32 v121, v122, v123
	v_pk_fma_f32 v[122:123], v[126:127], v[166:167], v[166:167] op_sel_hi:[1,0,0]
	v_pk_fma_f32 v[116:117], v[124:125], v[166:167], v[166:167] op_sel_hi:[1,0,0]
	v_rcp_f32_e32 v122, v122
	v_rcp_f32_e32 v123, v123
	v_rcp_f32_e32 v116, v116
	v_rcp_f32_e32 v117, v117
	v_lshl_or_b32 v170, s18, 7, v148
	v_pk_mul_f32 v[112:113], v[122:123], v[112:113]
	v_lshl_add_u32 v144, s36, 8, v146
	v_cvt_pk_bf16_f32 v122, v112, v113
	v_pk_mul_f32 v[112:113], v[116:117], v[114:115]
	v_ashrrev_i32_e32 v171, 31, v170
	v_cvt_pk_bf16_f32 v123, v112, v113
	v_mov_b64_e32 v[112:113], s[34:35]
	v_pk_mul_f32 v[124:125], v[244:245], v[108:109] op_sel:[1,0]
	v_exp_f32_e32 v124, v124
	v_exp_f32_e32 v125, v125
	v_pk_mul_f32 v[104:105], v[108:109], v[104:105]
	v_pk_mul_f32 v[108:109], v[244:245], v[110:111] op_sel:[1,0]
	v_mad_i64_i32 v[116:117], s[18:19], v144, s56, v[112:113]
	v_lshlrev_b64 v[114:115], 1, v[170:171]
	v_exp_f32_e32 v108, v108
	v_exp_f32_e32 v109, v109
	v_lshl_add_u64 v[216:217], v[116:117], 0, v[114:115]
	global_store_dwordx4 v[216:217], v[120:123], off
	s_mov_b32 s99, 0
	s_nop 0
	v_pk_fma_f32 v[108:109], v[108:109], v[164:165], v[164:165] op_sel:[0,1,1]
	v_pk_fma_f32 v[120:121], v[124:125], v[164:165], v[164:165] op_sel:[0,1,1]
	v_rcp_f32_e32 v108, v108
	v_rcp_f32_e32 v120, v120
	v_rcp_f32_e32 v121, v121
	v_rcp_f32_e32 v109, v109
	v_pk_mul_f32 v[106:107], v[110:111], v[106:107]
	v_pk_mul_f32 v[96:97], v[100:101], v[96:97]
	v_pk_mul_f32 v[104:105], v[120:121], v[104:105]
	v_pk_mul_f32 v[110:111], v[244:245], v[100:101] op_sel:[1,0]
	v_exp_f32_e32 v110, v110
	v_exp_f32_e32 v111, v111
	v_pk_mul_f32 v[106:107], v[108:109], v[106:107]
	v_pk_mul_f32 v[108:109], v[244:245], v[102:103] op_sel:[1,0]
	v_exp_f32_e32 v108, v108
	v_exp_f32_e32 v109, v109
	v_cvt_pk_bf16_f32 v104, v104, v105
	v_cvt_pk_bf16_f32 v105, v106, v107
	v_pk_fma_f32 v[106:107], v[110:111], v[164:165], v[164:165] op_sel:[0,1,1]
	v_pk_fma_f32 v[100:101], v[108:109], v[164:165], v[164:165] op_sel:[0,1,1]
	v_rcp_f32_e32 v106, v106
	v_rcp_f32_e32 v107, v107
	v_rcp_f32_e32 v100, v100
	v_rcp_f32_e32 v101, v101
	v_pk_mul_f32 v[98:99], v[102:103], v[98:99]
	v_pk_mul_f32 v[96:97], v[106:107], v[96:97]
	v_pk_mul_f32 v[88:89], v[92:93], v[88:89]
	v_cvt_pk_bf16_f32 v106, v96, v97
	v_pk_mul_f32 v[96:97], v[100:101], v[98:99]
	v_pk_mul_f32 v[90:91], v[94:95], v[90:91]
	v_cvt_pk_bf16_f32 v107, v96, v97
	s_nop 0
	v_pk_mul_f32 v[100:101], v[246:247], v[92:93] op_sel_hi:[0,1]
	v_exp_f32_e32 v100, v100
	v_exp_f32_e32 v101, v101
	v_pk_mul_f32 v[92:93], v[246:247], v[94:95] op_sel_hi:[0,1]
	v_exp_f32_e32 v92, v92
	v_exp_f32_e32 v93, v93
	v_pk_fma_f32 v[100:101], v[100:101], v[164:165], v[164:165] op_sel_hi:[1,0,0]
	s_mov_b32 s98, 0x16000
	v_lshl_add_u64 v[96:97], v[216:217], 0, s[98:99]
	v_rcp_f32_e32 v100, v100
	v_rcp_f32_e32 v101, v101
	v_pk_fma_f32 v[92:93], v[92:93], v[164:165], v[164:165] op_sel_hi:[1,0,0]
	global_store_dwordx4 v[96:97], v[104:107], off
	v_rcp_f32_e32 v92, v92
	v_rcp_f32_e32 v93, v93
	v_pk_mul_f32 v[88:89], v[100:101], v[88:89]
	v_pk_mul_f32 v[94:95], v[246:247], v[84:85] op_sel_hi:[0,1]
	v_exp_f32_e32 v94, v94
	v_exp_f32_e32 v95, v95
	v_pk_mul_f32 v[90:91], v[92:93], v[90:91]
	v_pk_mul_f32 v[92:93], v[246:247], v[86:87] op_sel_hi:[0,1]
	v_exp_f32_e32 v92, v92
	v_exp_f32_e32 v93, v93
	v_cvt_pk_bf16_f32 v88, v88, v89
	v_cvt_pk_bf16_f32 v89, v90, v91
	v_pk_fma_f32 v[90:91], v[94:95], v[164:165], v[164:165] op_sel_hi:[1,0,0]
	v_pk_mul_f32 v[80:81], v[84:85], v[80:81]
	v_rcp_f32_e32 v90, v90
	v_rcp_f32_e32 v91, v91
	v_pk_fma_f32 v[84:85], v[92:93], v[164:165], v[164:165] op_sel_hi:[1,0,0]
	v_pk_mul_f32 v[82:83], v[86:87], v[82:83]
	v_rcp_f32_e32 v84, v84
	v_rcp_f32_e32 v85, v85
	v_pk_mul_f32 v[80:81], v[90:91], v[80:81]
	v_pk_mul_f32 v[72:73], v[76:77], v[72:73]
	v_cvt_pk_bf16_f32 v90, v80, v81
	v_pk_mul_f32 v[80:81], v[84:85], v[82:83]
	v_pk_mul_f32 v[74:75], v[78:79], v[74:75]
	v_cvt_pk_bf16_f32 v91, v80, v81
	s_nop 0
	v_pk_mul_f32 v[84:85], v[246:247], v[76:77] op_sel:[1,0]
	v_exp_f32_e32 v84, v84
	v_exp_f32_e32 v85, v85
	v_pk_mul_f32 v[76:77], v[246:247], v[78:79] op_sel:[1,0]
	v_exp_f32_e32 v76, v76
	v_exp_f32_e32 v77, v77
	v_pk_fma_f32 v[84:85], v[84:85], v[162:163], v[162:163] op_sel:[0,1,1]
	s_mov_b32 s98, 0x2c000
	v_lshl_add_u64 v[80:81], v[216:217], 0, s[98:99]
	v_rcp_f32_e32 v84, v84
	v_rcp_f32_e32 v85, v85
	v_pk_fma_f32 v[76:77], v[76:77], v[162:163], v[162:163] op_sel:[0,1,1]
	global_store_dwordx4 v[80:81], v[88:91], off
	v_rcp_f32_e32 v76, v76
	v_rcp_f32_e32 v77, v77
	v_pk_mul_f32 v[72:73], v[84:85], v[72:73]
	v_pk_mul_f32 v[78:79], v[246:247], v[68:69] op_sel:[1,0]
	v_exp_f32_e32 v78, v78
	v_exp_f32_e32 v79, v79
	v_pk_mul_f32 v[74:75], v[76:77], v[74:75]
	v_pk_mul_f32 v[76:77], v[246:247], v[70:71] op_sel:[1,0]
	v_exp_f32_e32 v76, v76
	v_exp_f32_e32 v77, v77
	v_cvt_pk_bf16_f32 v72, v72, v73
	v_cvt_pk_bf16_f32 v73, v74, v75
	v_pk_fma_f32 v[74:75], v[78:79], v[162:163], v[162:163] op_sel:[0,1,1]
	v_pk_mul_f32 v[64:65], v[68:69], v[64:65]
	v_rcp_f32_e32 v74, v74
	v_rcp_f32_e32 v75, v75
	v_pk_fma_f32 v[68:69], v[76:77], v[162:163], v[162:163] op_sel:[0,1,1]
	v_pk_mul_f32 v[66:67], v[70:71], v[66:67]
	v_rcp_f32_e32 v68, v68
	v_rcp_f32_e32 v69, v69
	v_pk_mul_f32 v[64:65], v[74:75], v[64:65]
	v_pk_mul_f32 v[56:57], v[60:61], v[56:57]
	v_cvt_pk_bf16_f32 v74, v64, v65
	v_pk_mul_f32 v[64:65], v[68:69], v[66:67]
	v_pk_mul_f32 v[58:59], v[62:63], v[58:59]
	v_cvt_pk_bf16_f32 v75, v64, v65
	s_nop 0
	v_pk_mul_f32 v[68:69], v[248:249], v[60:61] op_sel_hi:[0,1]
	v_exp_f32_e32 v68, v68
	v_exp_f32_e32 v69, v69
	v_pk_mul_f32 v[60:61], v[248:249], v[62:63] op_sel_hi:[0,1]
	v_exp_f32_e32 v60, v60
	v_exp_f32_e32 v61, v61
	v_pk_fma_f32 v[68:69], v[68:69], v[162:163], v[162:163] op_sel_hi:[1,0,0]
	s_mov_b32 s98, 0x42000
	v_lshl_add_u64 v[64:65], v[216:217], 0, s[98:99]
	v_rcp_f32_e32 v68, v68
	v_rcp_f32_e32 v69, v69
	v_pk_fma_f32 v[60:61], v[60:61], v[162:163], v[162:163] op_sel_hi:[1,0,0]
	global_store_dwordx4 v[64:65], v[72:75], off
	v_rcp_f32_e32 v60, v60
	v_rcp_f32_e32 v61, v61
	v_pk_mul_f32 v[56:57], v[68:69], v[56:57]
	v_pk_mul_f32 v[62:63], v[248:249], v[52:53] op_sel_hi:[0,1]
	v_exp_f32_e32 v62, v62
	v_exp_f32_e32 v63, v63
	v_pk_mul_f32 v[58:59], v[60:61], v[58:59]
	v_pk_mul_f32 v[60:61], v[248:249], v[54:55] op_sel_hi:[0,1]
	v_exp_f32_e32 v60, v60
	v_exp_f32_e32 v61, v61
	v_cvt_pk_bf16_f32 v56, v56, v57
	v_cvt_pk_bf16_f32 v57, v58, v59
	v_pk_fma_f32 v[58:59], v[62:63], v[162:163], v[162:163] op_sel_hi:[1,0,0]
	v_pk_mul_f32 v[48:49], v[52:53], v[48:49]
	v_rcp_f32_e32 v58, v58
	v_rcp_f32_e32 v59, v59
	v_pk_fma_f32 v[52:53], v[60:61], v[162:163], v[162:163] op_sel_hi:[1,0,0]
	v_pk_mul_f32 v[50:51], v[54:55], v[50:51]
	v_rcp_f32_e32 v52, v52
	v_rcp_f32_e32 v53, v53
	v_pk_mul_f32 v[48:49], v[58:59], v[48:49]
	v_pk_mul_f32 v[40:41], v[44:45], v[40:41]
	v_cvt_pk_bf16_f32 v58, v48, v49
	v_pk_mul_f32 v[48:49], v[52:53], v[50:51]
	v_cvt_pk_bf16_f32 v59, v48, v49
	v_pk_mul_f32 v[52:53], v[248:249], v[44:45] op_sel:[1,0]
	v_exp_f32_e32 v52, v52
	v_exp_f32_e32 v53, v53
	v_pk_mul_f32 v[44:45], v[248:249], v[46:47] op_sel:[1,0]
	v_exp_f32_e32 v44, v44
	v_exp_f32_e32 v45, v45
	v_pk_fma_f32 v[52:53], v[52:53], v[160:161], v[160:161] op_sel:[0,1,1]
	s_mov_b32 s98, 0xb0000
	v_lshl_add_u64 v[48:49], v[216:217], 0, s[98:99]
	v_rcp_f32_e32 v52, v52
	v_rcp_f32_e32 v53, v53
	v_pk_fma_f32 v[44:45], v[44:45], v[160:161], v[160:161] op_sel:[0,1,1]
	global_store_dwordx4 v[48:49], v[56:59], off
	v_rcp_f32_e32 v44, v44
	v_rcp_f32_e32 v45, v45
	v_pk_mul_f32 v[42:43], v[46:47], v[42:43]
	v_pk_mul_f32 v[40:41], v[52:53], v[40:41]
	v_pk_mul_f32 v[46:47], v[248:249], v[36:37] op_sel:[1,0]
	v_exp_f32_e32 v46, v46
	v_exp_f32_e32 v47, v47
	v_pk_mul_f32 v[42:43], v[44:45], v[42:43]
	v_pk_mul_f32 v[44:45], v[248:249], v[38:39] op_sel:[1,0]
	v_exp_f32_e32 v44, v44
	v_exp_f32_e32 v45, v45
	v_cvt_pk_bf16_f32 v40, v40, v41
	v_cvt_pk_bf16_f32 v41, v42, v43
	v_pk_fma_f32 v[42:43], v[46:47], v[160:161], v[160:161] op_sel:[0,1,1]
	v_pk_mul_f32 v[32:33], v[36:37], v[32:33]
	v_rcp_f32_e32 v42, v42
	v_rcp_f32_e32 v43, v43
	v_pk_fma_f32 v[36:37], v[44:45], v[160:161], v[160:161] op_sel:[0,1,1]
	v_pk_mul_f32 v[34:35], v[38:39], v[34:35]
	v_rcp_f32_e32 v36, v36
	v_rcp_f32_e32 v37, v37
	v_pk_mul_f32 v[32:33], v[42:43], v[32:33]
	v_pk_mul_f32 v[24:25], v[28:29], v[24:25]
	v_cvt_pk_bf16_f32 v42, v32, v33
	v_pk_mul_f32 v[32:33], v[36:37], v[34:35]
	v_pk_mul_f32 v[26:27], v[30:31], v[26:27]
	v_cvt_pk_bf16_f32 v43, v32, v33
	s_nop 0
	v_pk_mul_f32 v[36:37], v[250:251], v[28:29] op_sel_hi:[0,1]
	v_exp_f32_e32 v36, v36
	v_exp_f32_e32 v37, v37
	v_pk_mul_f32 v[28:29], v[250:251], v[30:31] op_sel_hi:[0,1]
	v_exp_f32_e32 v28, v28
	v_exp_f32_e32 v29, v29
	v_pk_fma_f32 v[36:37], v[36:37], v[152:153], v[152:153] op_sel_hi:[1,0,0]
	s_mov_b32 s98, 0xc6000
	v_lshl_add_u64 v[32:33], v[216:217], 0, s[98:99]
	v_rcp_f32_e32 v36, v36
	v_rcp_f32_e32 v37, v37
	v_pk_fma_f32 v[28:29], v[28:29], v[152:153], v[152:153] op_sel_hi:[1,0,0]
	global_store_dwordx4 v[32:33], v[40:43], off
	v_rcp_f32_e32 v28, v28
	v_rcp_f32_e32 v29, v29
	v_pk_mul_f32 v[24:25], v[36:37], v[24:25]
	v_pk_mul_f32 v[30:31], v[250:251], v[20:21] op_sel_hi:[0,1]
	v_exp_f32_e32 v30, v30
	v_exp_f32_e32 v31, v31
	v_pk_mul_f32 v[26:27], v[28:29], v[26:27]
	v_pk_mul_f32 v[28:29], v[250:251], v[22:23] op_sel_hi:[0,1]
	v_exp_f32_e32 v28, v28
	v_exp_f32_e32 v29, v29
	v_cvt_pk_bf16_f32 v24, v24, v25
	v_cvt_pk_bf16_f32 v25, v26, v27
	v_pk_fma_f32 v[26:27], v[30:31], v[152:153], v[152:153] op_sel_hi:[1,0,0]
	v_pk_mul_f32 v[16:17], v[20:21], v[16:17]
	v_rcp_f32_e32 v26, v26
	v_rcp_f32_e32 v27, v27
	v_pk_fma_f32 v[20:21], v[28:29], v[152:153], v[152:153] op_sel_hi:[1,0,0]
	v_pk_mul_f32 v[18:19], v[22:23], v[18:19]
	v_rcp_f32_e32 v20, v20
	v_rcp_f32_e32 v21, v21
	v_pk_mul_f32 v[16:17], v[26:27], v[16:17]
	v_pk_mul_f32 v[8:9], v[12:13], v[8:9]
	v_cvt_pk_bf16_f32 v26, v16, v17
	v_pk_mul_f32 v[16:17], v[20:21], v[18:19]
	v_pk_mul_f32 v[10:11], v[14:15], v[10:11]
	v_cvt_pk_bf16_f32 v27, v16, v17
	s_nop 0
	v_pk_mul_f32 v[20:21], v[250:251], v[12:13] op_sel:[1,0]
	v_exp_f32_e32 v20, v20
	v_exp_f32_e32 v21, v21
	v_pk_mul_f32 v[12:13], v[250:251], v[14:15] op_sel:[1,0]
	v_exp_f32_e32 v12, v12
	v_exp_f32_e32 v13, v13
	v_pk_fma_f32 v[20:21], v[20:21], v[148:149], v[148:149] op_sel:[0,1,1]
	s_mov_b32 s98, 0xdc000
	v_lshl_add_u64 v[16:17], v[216:217], 0, s[98:99]
	v_rcp_f32_e32 v20, v20
	v_rcp_f32_e32 v21, v21
	v_pk_fma_f32 v[12:13], v[12:13], v[148:149], v[148:149] op_sel:[0,1,1]
	global_store_dwordx4 v[16:17], v[24:27], off
	v_rcp_f32_e32 v12, v12
	v_rcp_f32_e32 v13, v13
	v_pk_mul_f32 v[8:9], v[20:21], v[8:9]
	v_pk_mul_f32 v[14:15], v[250:251], v[4:5] op_sel:[1,0]
	v_exp_f32_e32 v14, v14
	v_exp_f32_e32 v15, v15
	v_pk_mul_f32 v[10:11], v[12:13], v[10:11]
	v_pk_mul_f32 v[12:13], v[250:251], v[6:7] op_sel:[1,0]
	v_exp_f32_e32 v12, v12
	v_exp_f32_e32 v13, v13
	v_cvt_pk_bf16_f32 v8, v8, v9
	v_cvt_pk_bf16_f32 v9, v10, v11
	v_pk_fma_f32 v[10:11], v[14:15], v[148:149], v[148:149] op_sel:[0,1,1]
	v_pk_mul_f32 v[0:1], v[4:5], v[0:1]
	v_rcp_f32_e32 v10, v10
	v_rcp_f32_e32 v11, v11
	v_pk_fma_f32 v[4:5], v[12:13], v[148:149], v[148:149] op_sel:[0,1,1]
	v_pk_mul_f32 v[2:3], v[6:7], v[2:3]
	v_rcp_f32_e32 v4, v4
	v_rcp_f32_e32 v5, v5
	v_pk_mul_f32 v[0:1], v[10:11], v[0:1]
	s_andn2_b64 vcc, exec, s[0:1]
	v_cvt_pk_bf16_f32 v10, v0, v1
	v_pk_mul_f32 v[0:1], v[4:5], v[2:3]
	s_mov_b64 s[0:1], -1
	v_cvt_pk_bf16_f32 v11, v0, v1
	s_mov_b32 s98, 0xf2000
	v_lshl_add_u64 v[0:1], v[216:217], 0, s[98:99]
	global_store_dwordx4 v[0:1], v[8:11], off
	s_cbranch_vccnz .LBB0_681
	s_andn2_b64 vcc, exec, s[6:7]
	s_cbranch_vccnz .LBB0_680
	s_barrier
	s_branch .LBB0_680
